# v9 plus: ctx-row partial-slab loads batched (counted vmcnt); phase-0 GEMV loads issued ahead; SwiGLU epilogue as independent chains; s_nop after scalar base updates
# speedup vs baseline: 1.0218x; 1.0118x over previous
; #define PG8_STAGE(bufoff, gbase, voff) do { _Pragma("unroll") for (int _i = 0; _i < 2; ++_i) \
;         __builtin_amdgcn_global_load_lds((const unsigned*)((const char*)(gbase) + (voff)[_i]), (LAS unsigned*)(lds + (bufoff) + ldsw + _i * 8192), 16, 0, 0); } while (0)
; #define PG8_LDA(dst, b, h) do { _Pragma("unroll") for (int m = 0; m < 4; ++m) _Pragma("unroll") for (int k = 0; k < 2; ++k) dst[m][k] = *(const LAS bf16x8*)(lds + PG8_SA(b, h) + aoff + m * 2048 + k * 1024); } while (0)
; #define PG8_LDB(dst, b, h) do { _Pragma("unroll") for (int n = 0; n < 2; ++n) _Pragma("unroll") for (int k = 0; k < 2; ++k) dst[n][k] = *(const LAS bf16x8*)(lds + PG8_SB(b, h) + boff + n * 2048 + k * 1024); } while (0)
; #define PG8_WAIT_V(n) asm volatile("s_waitcnt vmcnt(" #n ")" ::: "memory")
; #define PG8_WAIT_L(n) asm volatile("s_waitcnt lgkmcnt(" #n ")" ::: "memory")
; #define PG8_BAR __builtin_amdgcn_s_barrier()
; #define PG8_SCHED __builtin_amdgcn_sched_barrier(0)
; template <class Epi>
; __device__ __forceinline__ void gemm_phase(LAS unsigned char* lds, const Gemm g, const StaticOrder& S, const Epi& E) {
;     ...
;         for (int t = 0; t < nt; t += 2) {
;             const bool last = (t == nt - 2);
;             const char* a1 = cA + (size_t)(t + 1) * kstep;
;             const char* a2 = last ? nA : cA + (size_t)(t + 2) * kstep; const char* b2 = last ? nB : cB + (size_t)(t + 2) * kstep;
;             const char* a3 = a2 + kstep; const char* b3 = b2 + kstep;
;             PG8_LDB(B0, 0, 0); PG8_SCHED; PG8_LDA(At, 0, 0); PG8_STAGE(PG8_SA(1, 1), a1 + hstep, voffA);
;             PG8_WAIT_L(8); PG8_BAR; PG8_WAIT_L(0); PG8_MMA(0, 0, At, B0); PG8_BAR; PG8_SCHED;
;             PG8_LDB(B1, 0, 1); PG8_STAGE(PG8_SB(0, 0), b2, voffB);
;             PG8_BAR; PG8_WAIT_L(0); PG8_MMA(0, 1, At, B1); PG8_BAR;
;             PG8_LDA(At, 0, 1); PG8_STAGE(PG8_SA(0, 0), a2, voffA);
;             PG8_BAR; PG8_WAIT_L(0); PG8_MMA(1, 0, At, B0); PG8_BAR; PG8_SCHED;
;             PG8_STAGE(PG8_SB(0, 1), b2 + hstep, voffB);
;             PG8_WAIT_V(6); PG8_BAR; PG8_MMA(1, 1, At, B1); PG8_BAR;
;             PG8_LDB(B0, 1, 0); PG8_SCHED; PG8_LDA(At, 1, 0); PG8_STAGE(PG8_SA(0, 1), a2 + hstep, voffA);
;             PG8_WAIT_L(8); PG8_BAR; PG8_WAIT_L(0); PG8_MMA(0, 0, At, B0); PG8_BAR; PG8_SCHED;
.LBB0_1151:
	s_add_i32 s46, s22, 2
	s_add_u32 s24, s20, 0x80
	s_addc_u32 s23, s21, 0
	s_add_i32 s47, 0, 0x10000
	v_add_u32_e32 v135, s47, v164
	ds_read_b128 v[142:145], v135
	ds_read_b128 v[146:149], v135 offset:1024
	ds_read_b128 v[150:153], v135 offset:2048
	ds_read_b128 v[154:157], v135 offset:3072
	s_cmp_eq_u32 s57, s22
	s_cselect_b32 s22, s16, s24
	s_cselect_b32 s23, s17, s23
	s_cselect_b32 s25, s19, s45
	s_cselect_b32 s24, s18, s44
	v_lshl_add_u64 v[162:163], s[20:21], 0, v[138:139]
	s_add_i32 m0, s40, 0xc000
	ds_read_b128 v[158:161], v166
	ds_read_b128 v[168:171], v166 offset:1024
	ds_read_b128 v[172:175], v166 offset:2048
	ds_read_b128 v[186:189], v166 offset:3072
	ds_read_b128 v[210:213], v166 offset:4096
	ds_read_b128 v[214:217], v166 offset:5120
	ds_read_b128 v[218:221], v166 offset:6144
	ds_read_b128 v[222:225], v166 offset:7168
	global_load_lds_dwordx4 v[162:163], off
	v_lshl_add_u64 v[162:163], s[20:21], 0, v[140:141]
	s_add_i32 m0, s40, 0xe000
	s_nop 0
	global_load_lds_dwordx4 v[162:163], off
	s_waitcnt lgkmcnt(8)
	s_barrier
	s_waitcnt lgkmcnt(0)
	s_setprio 1
	s_waitcnt lgkmcnt(0)
	v_mfma_f32_16x16x32_bf16 v[126:129], v[142:145], v[158:161], v[126:129]
	v_mfma_f32_16x16x32_bf16 v[122:125], v[150:153], v[158:161], v[122:125]
	v_mfma_f32_16x16x32_bf16 v[110:113], v[142:145], v[172:175], v[110:113]
	v_mfma_f32_16x16x32_bf16 v[106:109], v[150:153], v[172:175], v[106:109]
	v_mfma_f32_16x16x32_bf16 v[92:95], v[142:145], v[210:213], v[92:95]
	v_mfma_f32_16x16x32_bf16 v[88:91], v[150:153], v[210:213], v[88:91]
	v_mfma_f32_16x16x32_bf16 v[76:79], v[142:145], v[218:221], v[76:79]
	v_mfma_f32_16x16x32_bf16 v[72:75], v[150:153], v[218:221], v[72:75]
	v_mfma_f32_16x16x32_bf16 v[126:129], v[146:149], v[168:171], v[126:129]
	v_mfma_f32_16x16x32_bf16 v[122:125], v[154:157], v[168:171], v[122:125]
	v_mfma_f32_16x16x32_bf16 v[110:113], v[146:149], v[186:189], v[110:113]
	v_mfma_f32_16x16x32_bf16 v[106:109], v[154:157], v[186:189], v[106:109]
	v_mfma_f32_16x16x32_bf16 v[92:95], v[146:149], v[214:217], v[92:95]
	v_mfma_f32_16x16x32_bf16 v[88:91], v[154:157], v[214:217], v[88:91]
	v_mfma_f32_16x16x32_bf16 v[76:79], v[146:149], v[222:225], v[76:79]
	v_mfma_f32_16x16x32_bf16 v[72:75], v[154:157], v[222:225], v[72:75]
	s_setprio 0
	s_barrier
	s_add_i32 s67, 0, 0x14000
	s_add_i32 s47, s47, s31
	v_add_u32_e32 v135, s67, v164
	v_lshl_add_u64 v[162:163], s[24:25], 0, v[132:133]
	s_mov_b32 m0, s47
	ds_read_b128 v[226:229], v135
	ds_read_b128 v[230:233], v135 offset:1024
	ds_read_b128 v[234:237], v135 offset:2048
	ds_read_b128 v[238:241], v135 offset:3072
	global_load_lds_dwordx4 v[162:163], off
	v_lshl_add_u64 v[176:177], s[24:25], 0, v[130:131]
	s_add_i32 m0, s47, 0x2000
	s_nop 0
	global_load_lds_dwordx4 v[176:177], off
	s_barrier
	s_waitcnt lgkmcnt(0)
	s_setprio 1
	s_waitcnt lgkmcnt(0)
	v_mfma_f32_16x16x32_bf16 v[118:121], v[226:229], v[158:161], v[118:121]
	v_mfma_f32_16x16x32_bf16 v[114:117], v[234:237], v[158:161], v[114:117]
	v_mfma_f32_16x16x32_bf16 v[102:105], v[226:229], v[172:175], v[102:105]
	v_mfma_f32_16x16x32_bf16 v[98:101], v[234:237], v[172:175], v[98:101]
	v_mfma_f32_16x16x32_bf16 v[84:87], v[226:229], v[210:213], v[84:87]
	v_mfma_f32_16x16x32_bf16 v[80:83], v[234:237], v[210:213], v[80:83]
	v_mfma_f32_16x16x32_bf16 v[68:71], v[226:229], v[218:221], v[68:71]
	v_mfma_f32_16x16x32_bf16 v[64:67], v[234:237], v[218:221], v[64:67]
	v_mfma_f32_16x16x32_bf16 v[118:121], v[230:233], v[168:171], v[118:121]
	v_mfma_f32_16x16x32_bf16 v[114:117], v[238:241], v[168:171], v[114:117]
	v_mfma_f32_16x16x32_bf16 v[102:105], v[230:233], v[186:189], v[102:105]
	v_mfma_f32_16x16x32_bf16 v[98:101], v[238:241], v[186:189], v[98:101]
	v_mfma_f32_16x16x32_bf16 v[84:87], v[230:233], v[214:217], v[84:87]
	v_mfma_f32_16x16x32_bf16 v[80:83], v[238:241], v[214:217], v[80:83]
	v_mfma_f32_16x16x32_bf16 v[68:71], v[230:233], v[222:225], v[68:71]
	v_mfma_f32_16x16x32_bf16 v[64:67], v[238:241], v[222:225], v[64:67]
	s_setprio 0
	s_mov_b32 m0, s40
	v_lshl_add_u64 v[198:199], s[22:23], 0, v[132:133]
	s_barrier
	ds_read_b128 v[158:161], v166 offset:16384
	ds_read_b128 v[168:171], v166 offset:17408
	ds_read_b128 v[172:175], v166 offset:18432
	ds_read_b128 v[186:189], v166 offset:19456
	ds_read_b128 v[210:213], v166 offset:20480
	ds_read_b128 v[214:217], v166 offset:21504
	ds_read_b128 v[218:221], v166 offset:22528
	ds_read_b128 v[222:225], v166 offset:23552
	global_load_lds_dwordx4 v[198:199], off
	v_lshl_add_u64 v[200:201], s[22:23], 0, v[130:131]
	s_mov_b32 m0, s41
	s_nop 0
	global_load_lds_dwordx4 v[200:201], off
	s_barrier
	s_waitcnt lgkmcnt(0)
	s_setprio 1
	s_waitcnt lgkmcnt(0)
	v_mfma_f32_16x16x32_bf16 v[60:63], v[142:145], v[158:161], v[60:63]
	v_mfma_f32_16x16x32_bf16 v[56:59], v[150:153], v[158:161], v[56:59]
	v_mfma_f32_16x16x32_bf16 v[44:47], v[142:145], v[172:175], v[44:47]
	v_mfma_f32_16x16x32_bf16 v[40:43], v[150:153], v[172:175], v[40:43]
	v_mfma_f32_16x16x32_bf16 v[28:31], v[142:145], v[210:213], v[28:31]
	v_mfma_f32_16x16x32_bf16 v[24:27], v[150:153], v[210:213], v[24:27]
	v_mfma_f32_16x16x32_bf16 v[12:15], v[142:145], v[218:221], v[12:15]
	v_mfma_f32_16x16x32_bf16 v[8:11], v[150:153], v[218:221], v[8:11]
	v_mfma_f32_16x16x32_bf16 v[60:63], v[146:149], v[168:171], v[60:63]
	v_mfma_f32_16x16x32_bf16 v[56:59], v[154:157], v[168:171], v[56:59]
	v_mfma_f32_16x16x32_bf16 v[44:47], v[146:149], v[186:189], v[44:47]
	v_mfma_f32_16x16x32_bf16 v[40:43], v[154:157], v[186:189], v[40:43]
	v_mfma_f32_16x16x32_bf16 v[28:31], v[146:149], v[214:217], v[28:31]
	v_mfma_f32_16x16x32_bf16 v[24:27], v[154:157], v[214:217], v[24:27]
	v_mfma_f32_16x16x32_bf16 v[12:15], v[146:149], v[222:225], v[12:15]
	v_mfma_f32_16x16x32_bf16 v[8:11], v[154:157], v[222:225], v[8:11]
	s_setprio 0
	s_barrier
; #define PG8_STAGE(bufoff, gbase, voff) do { _Pragma("unroll") for (int _i = 0; _i < 2; ++_i) \
;         __builtin_amdgcn_global_load_lds((const unsigned*)((const char*)(gbase) + (voff)[_i]), (LAS unsigned*)(lds + (bufoff) + ldsw + _i * 8192), 16, 0, 0); } while (0)
; #define PG8_LDA(dst, b, h) do { _Pragma("unroll") for (int m = 0; m < 4; ++m) _Pragma("unroll") for (int k = 0; k < 2; ++k) dst[m][k] = *(const LAS bf16x8*)(lds + PG8_SA(b, h) + aoff + m * 2048 + k * 1024); } while (0)
; #define PG8_LDB(dst, b, h) do { _Pragma("unroll") for (int n = 0; n < 2; ++n) _Pragma("unroll") for (int k = 0; k < 2; ++k) dst[n][k] = *(const LAS bf16x8*)(lds + PG8_SB(b, h) + boff + n * 2048 + k * 1024); } while (0)
; #define PG8_MMA(ai, bj, At, Bt) do { __builtin_amdgcn_s_setprio(1); _Pragma("unroll") for (int m = 0; m < 4; ++m) _Pragma("unroll") for (int n = 0; n < 2; ++n) _Pragma("unroll") for (int k = 0; k < 2; ++k) \
;         acc[ai][bj][m][n] = __builtin_amdgcn_mfma_f32_16x16x32_bf16(Bt[n][k], At[m][k], acc[ai][bj][m][n], 0, 0, 0); __builtin_amdgcn_s_setprio(0); } while (0)
; #define PG8_WAIT_V(n) asm volatile("s_waitcnt vmcnt(" #n ")" ::: "memory")
; #define PG8_WAIT_L(n) asm volatile("s_waitcnt lgkmcnt(" #n ")" ::: "memory")
; #define PG8_BAR __builtin_amdgcn_s_barrier()
; #define PG8_SCHED __builtin_amdgcn_sched_barrier(0)
; template <class Epi>
; __device__ __forceinline__ void gemm_phase(LAS unsigned char* lds, const Gemm g, const StaticOrder& S, const Epi& E) {
;     ...
;             PG8_LDB(B0, 1, 0); PG8_SCHED; PG8_LDA(At, 1, 0); PG8_STAGE(PG8_SA(0, 1), a2 + hstep, voffA);
;             PG8_WAIT_L(8); PG8_BAR; PG8_WAIT_L(0); PG8_MMA(0, 0, At, B0); PG8_BAR; PG8_SCHED;
;             PG8_LDB(B1, 1, 1); PG8_STAGE(PG8_SB(1, 0), b3, voffB);
;             PG8_BAR; PG8_WAIT_L(0); PG8_MMA(0, 1, At, B1); PG8_BAR;
;             PG8_LDA(At, 1, 1); PG8_STAGE(PG8_SA(1, 0), a3, voffA);
;             PG8_BAR; PG8_WAIT_L(0); PG8_MMA(1, 0, At, B0); PG8_BAR; PG8_SCHED;
;             PG8_STAGE(PG8_SB(1, 1), b3 + hstep, voffB);
;             PG8_WAIT_V(6); PG8_BAR; PG8_MMA(1, 1, At, B1); PG8_BAR;
	s_add_u32 s24, s24, s14
	s_addc_u32 s25, s25, 0
	s_add_i32 s47, s67, s31
	v_lshl_add_u64 v[242:243], s[24:25], 0, v[132:133]
	s_mov_b32 m0, s47
	v_lshl_add_u64 v[244:245], s[24:25], 0, v[130:131]
	global_load_lds_dwordx4 v[242:243], off
	s_add_i32 m0, s47, 0x2000
	s_nop 0
	global_load_lds_dwordx4 v[244:245], off
	s_waitcnt vmcnt(6)
	s_barrier
	s_setprio 1
	v_mfma_f32_16x16x32_bf16 v[52:55], v[226:229], v[158:161], v[52:55]
	v_mfma_f32_16x16x32_bf16 v[48:51], v[234:237], v[158:161], v[48:51]
	v_mfma_f32_16x16x32_bf16 v[36:39], v[226:229], v[172:175], v[36:39]
	v_mfma_f32_16x16x32_bf16 v[32:35], v[234:237], v[172:175], v[32:35]
	v_mfma_f32_16x16x32_bf16 v[20:23], v[226:229], v[210:213], v[20:23]
	v_mfma_f32_16x16x32_bf16 v[16:19], v[234:237], v[210:213], v[16:19]
	v_mfma_f32_16x16x32_bf16 v[4:7], v[226:229], v[218:221], v[4:7]
	v_mfma_f32_16x16x32_bf16 v[0:3], v[234:237], v[218:221], v[0:3]
	v_mfma_f32_16x16x32_bf16 v[52:55], v[230:233], v[168:171], v[52:55]
	v_mfma_f32_16x16x32_bf16 v[48:51], v[238:241], v[168:171], v[48:51]
	v_mfma_f32_16x16x32_bf16 v[36:39], v[230:233], v[186:189], v[36:39]
	v_mfma_f32_16x16x32_bf16 v[32:35], v[238:241], v[186:189], v[32:35]
	v_mfma_f32_16x16x32_bf16 v[20:23], v[230:233], v[214:217], v[20:23]
	v_mfma_f32_16x16x32_bf16 v[16:19], v[238:241], v[214:217], v[16:19]
	v_mfma_f32_16x16x32_bf16 v[4:7], v[230:233], v[222:225], v[4:7]
	v_mfma_f32_16x16x32_bf16 v[0:3], v[238:241], v[222:225], v[0:3]
	s_setprio 0
	s_add_i32 s24, 0, 0x18000
	v_add_u32_e32 v135, s24, v164
	s_barrier
	ds_read_b128 v[142:145], v135
	ds_read_b128 v[146:149], v135 offset:1024
	ds_read_b128 v[150:153], v135 offset:2048
	ds_read_b128 v[154:157], v135 offset:3072
	s_add_u32 s22, s22, s14
	s_addc_u32 s23, s23, 0
	s_mov_b32 m0, s48
	v_lshl_add_u64 v[226:227], s[22:23], 0, v[132:133]
	ds_read_b128 v[158:161], v166 offset:32768
	ds_read_b128 v[168:171], v166 offset:33792
	ds_read_b128 v[172:175], v166 offset:34816
	ds_read_b128 v[186:189], v166 offset:35840
	ds_read_b128 v[210:213], v166 offset:36864
	ds_read_b128 v[214:217], v166 offset:37888
	ds_read_b128 v[218:221], v166 offset:38912
	ds_read_b128 v[222:225], v166 offset:39936
	global_load_lds_dwordx4 v[226:227], off
	v_lshl_add_u64 v[226:227], s[22:23], 0, v[130:131]
	s_mov_b32 m0, s49
	s_nop 0
	global_load_lds_dwordx4 v[226:227], off
	s_waitcnt lgkmcnt(8)
	s_barrier
	s_waitcnt lgkmcnt(0)
	s_setprio 1
	s_waitcnt lgkmcnt(0)
	v_mfma_f32_16x16x32_bf16 v[126:129], v[142:145], v[158:161], v[126:129]
	v_mfma_f32_16x16x32_bf16 v[122:125], v[150:153], v[158:161], v[122:125]
	v_mfma_f32_16x16x32_bf16 v[110:113], v[142:145], v[172:175], v[110:113]
	v_mfma_f32_16x16x32_bf16 v[106:109], v[150:153], v[172:175], v[106:109]
	v_mfma_f32_16x16x32_bf16 v[92:95], v[142:145], v[210:213], v[92:95]
	v_mfma_f32_16x16x32_bf16 v[88:91], v[150:153], v[210:213], v[88:91]
	v_mfma_f32_16x16x32_bf16 v[76:79], v[142:145], v[218:221], v[76:79]
	v_mfma_f32_16x16x32_bf16 v[72:75], v[150:153], v[218:221], v[72:75]
	v_mfma_f32_16x16x32_bf16 v[126:129], v[146:149], v[168:171], v[126:129]
	v_mfma_f32_16x16x32_bf16 v[122:125], v[154:157], v[168:171], v[122:125]
	v_mfma_f32_16x16x32_bf16 v[110:113], v[146:149], v[186:189], v[110:113]
	v_mfma_f32_16x16x32_bf16 v[106:109], v[154:157], v[186:189], v[106:109]
	v_mfma_f32_16x16x32_bf16 v[92:95], v[146:149], v[214:217], v[92:95]
	v_mfma_f32_16x16x32_bf16 v[88:91], v[154:157], v[214:217], v[88:91]
	v_mfma_f32_16x16x32_bf16 v[76:79], v[146:149], v[222:225], v[76:79]
	v_mfma_f32_16x16x32_bf16 v[72:75], v[154:157], v[222:225], v[72:75]
	s_setprio 0
	s_barrier
	s_add_i32 s22, 0, 0x1c000
	s_add_i32 s23, s24, s31
	v_add_u32_e32 v135, s22, v164
	v_lshl_add_u64 v[162:163], v[162:163], 0, s[86:87]
	s_mov_b32 m0, s23
	ds_read_b128 v[226:229], v135
	ds_read_b128 v[230:233], v135 offset:1024
	ds_read_b128 v[234:237], v135 offset:2048
	ds_read_b128 v[238:241], v135 offset:3072
	global_load_lds_dwordx4 v[162:163], off
	v_lshl_add_u64 v[162:163], v[176:177], 0, s[86:87]
	s_add_i32 m0, s23, 0x2000
	s_nop 0
	global_load_lds_dwordx4 v[162:163], off
	s_barrier
	s_waitcnt lgkmcnt(0)
	s_setprio 1
	s_waitcnt lgkmcnt(0)
	v_mfma_f32_16x16x32_bf16 v[118:121], v[226:229], v[158:161], v[118:121]
	v_mfma_f32_16x16x32_bf16 v[114:117], v[234:237], v[158:161], v[114:117]
	v_mfma_f32_16x16x32_bf16 v[102:105], v[226:229], v[172:175], v[102:105]
	v_mfma_f32_16x16x32_bf16 v[98:101], v[234:237], v[172:175], v[98:101]
	v_mfma_f32_16x16x32_bf16 v[84:87], v[226:229], v[210:213], v[84:87]
	v_mfma_f32_16x16x32_bf16 v[80:83], v[234:237], v[210:213], v[80:83]
	v_mfma_f32_16x16x32_bf16 v[68:71], v[226:229], v[218:221], v[68:71]
	v_mfma_f32_16x16x32_bf16 v[64:67], v[234:237], v[218:221], v[64:67]
	v_mfma_f32_16x16x32_bf16 v[118:121], v[230:233], v[168:171], v[118:121]
	v_mfma_f32_16x16x32_bf16 v[114:117], v[238:241], v[168:171], v[114:117]
	v_mfma_f32_16x16x32_bf16 v[102:105], v[230:233], v[186:189], v[102:105]
	v_mfma_f32_16x16x32_bf16 v[98:101], v[238:241], v[186:189], v[98:101]
	v_mfma_f32_16x16x32_bf16 v[84:87], v[230:233], v[214:217], v[84:87]
	v_mfma_f32_16x16x32_bf16 v[80:83], v[238:241], v[214:217], v[80:83]
	v_mfma_f32_16x16x32_bf16 v[68:71], v[230:233], v[222:225], v[68:71]
	v_mfma_f32_16x16x32_bf16 v[64:67], v[238:241], v[222:225], v[64:67]
	s_setprio 0
	s_mov_b32 m0, s53
	v_lshl_add_u64 v[162:163], v[198:199], 0, s[86:87]
	s_barrier
	ds_read_b128 v[158:161], v166 offset:49152
	ds_read_b128 v[168:171], v166 offset:50176
	ds_read_b128 v[172:175], v166 offset:51200
	ds_read_b128 v[186:189], v166 offset:52224
	ds_read_b128 v[210:213], v166 offset:53248
	ds_read_b128 v[214:217], v166 offset:54272
	ds_read_b128 v[218:221], v166 offset:55296
	ds_read_b128 v[222:225], v166 offset:56320
	global_load_lds_dwordx4 v[162:163], off
	v_lshl_add_u64 v[162:163], v[200:201], 0, s[86:87]
	s_mov_b32 m0, s54
	s_nop 0
	global_load_lds_dwordx4 v[162:163], off
	s_barrier
; #define PG8_STAGE(bufoff, gbase, voff) do { _Pragma("unroll") for (int _i = 0; _i < 2; ++_i) \
;         __builtin_amdgcn_global_load_lds((const unsigned*)((const char*)(gbase) + (voff)[_i]), (LAS unsigned*)(lds + (bufoff) + ldsw + _i * 8192), 16, 0, 0); } while (0)
; #define PG8_MMA(ai, bj, At, Bt) do { __builtin_amdgcn_s_setprio(1); _Pragma("unroll") for (int m = 0; m < 4; ++m) _Pragma("unroll") for (int n = 0; n < 2; ++n) _Pragma("unroll") for (int k = 0; k < 2; ++k) \
;         acc[ai][bj][m][n] = __builtin_amdgcn_mfma_f32_16x16x32_bf16(Bt[n][k], At[m][k], acc[ai][bj][m][n], 0, 0, 0); __builtin_amdgcn_s_setprio(0); } while (0)
; #define PG8_WAIT_V(n) asm volatile("s_waitcnt vmcnt(" #n ")" ::: "memory")
; #define PG8_BAR __builtin_amdgcn_s_barrier()
; template <class Epi>
; __device__ __forceinline__ void gemm_phase(LAS unsigned char* lds, const Gemm g, const StaticOrder& S, const Epi& E) {
;     ...
;             PG8_BAR; PG8_WAIT_L(0); PG8_MMA(1, 0, At, B0); PG8_BAR; PG8_SCHED;
;             PG8_STAGE(PG8_SB(1, 1), b3 + hstep, voffB);
;             PG8_WAIT_V(6); PG8_BAR; PG8_MMA(1, 1, At, B1); PG8_BAR;
;         }
;         E(acc, cur, wr, wc, fr, fq);
;         if (!has_next) break;
;     __device__ __forceinline__ void operator()(const f32x4 (&acc)[2][2][4][2], const pg8::Unit& u, int wr, int wc, int fr, int fq) const {
;         const bool isctx = u.pm >= 64; const int b = isctx ? 8 : (u.pm >> 3);
;         const int row0 = (isctx ? (u.pm - 64) : u.pm) * 256 + wr * 64 + fr, col0 = u.pn * 256 + wc * 32 + 4 * fq;
;         const float* gp = mod + (size_t)(b * NMOD + gidx) * DM + col0;
;         const float* rb = isctx ? resid_c : resid_l; float* ob = isctx ? out_c : out_l;
;         f32x4 gv[2][2];
; #pragma unroll
;         for (int bj = 0; bj < 2; ++bj)
; #pragma unroll
;             for (int n = 0; n < 2; ++n) gv[bj][n] = *(const f32x4*)(gp + bj * 128 + n * 16) * coef;
; #pragma unroll
;         for (int ai = 0; ai < 2; ++ai)
; #pragma unroll
;             for (int m = 0; m < 4; ++m) {
;                 const size_t o = (size_t)(row0 + ai * 128 + m * 16) * DM + col0;
; #pragma unroll
;                 for (int bj = 0; bj < 2; ++bj)
; #pragma unroll
;                     for (int n = 0; n < 2; ++n) { const f32x4 r = *(const f32x4*)(rb + o + bj * 128 + n * 16); *(f32x4*)(ob + o + bj * 128 + n * 16) = r + gv[bj][n] * acc[ai][bj][m][n]; }
	s_waitcnt lgkmcnt(0)
	s_setprio 1
	s_waitcnt lgkmcnt(0)
	v_mfma_f32_16x16x32_bf16 v[60:63], v[142:145], v[158:161], v[60:63]
	v_mfma_f32_16x16x32_bf16 v[56:59], v[150:153], v[158:161], v[56:59]
	v_mfma_f32_16x16x32_bf16 v[44:47], v[142:145], v[172:175], v[44:47]
	v_mfma_f32_16x16x32_bf16 v[40:43], v[150:153], v[172:175], v[40:43]
	v_mfma_f32_16x16x32_bf16 v[28:31], v[142:145], v[210:213], v[28:31]
	v_mfma_f32_16x16x32_bf16 v[24:27], v[150:153], v[210:213], v[24:27]
	v_mfma_f32_16x16x32_bf16 v[12:15], v[142:145], v[218:221], v[12:15]
	v_mfma_f32_16x16x32_bf16 v[8:11], v[150:153], v[218:221], v[8:11]
	v_mfma_f32_16x16x32_bf16 v[60:63], v[146:149], v[168:171], v[60:63]
	v_mfma_f32_16x16x32_bf16 v[56:59], v[154:157], v[168:171], v[56:59]
	v_mfma_f32_16x16x32_bf16 v[44:47], v[146:149], v[186:189], v[44:47]
	v_mfma_f32_16x16x32_bf16 v[40:43], v[154:157], v[186:189], v[40:43]
	v_mfma_f32_16x16x32_bf16 v[28:31], v[146:149], v[214:217], v[28:31]
	v_mfma_f32_16x16x32_bf16 v[24:27], v[154:157], v[214:217], v[24:27]
	v_mfma_f32_16x16x32_bf16 v[12:15], v[146:149], v[222:225], v[12:15]
	v_mfma_f32_16x16x32_bf16 v[8:11], v[154:157], v[222:225], v[8:11]
	s_setprio 0
	s_barrier
	s_add_i32 s22, s22, s31
	v_lshl_add_u64 v[142:143], v[242:243], 0, s[86:87]
	s_mov_b32 m0, s22
	s_nop 0
	global_load_lds_dwordx4 v[142:143], off
	v_lshl_add_u64 v[142:143], v[244:245], 0, s[86:87]
	s_add_i32 m0, s22, 0x2000
	s_nop 0
	global_load_lds_dwordx4 v[142:143], off
	s_waitcnt vmcnt(6)
	s_barrier
	s_setprio 1
	v_mfma_f32_16x16x32_bf16 v[52:55], v[226:229], v[158:161], v[52:55]
	v_mfma_f32_16x16x32_bf16 v[48:51], v[234:237], v[158:161], v[48:51]
	v_mfma_f32_16x16x32_bf16 v[36:39], v[226:229], v[172:175], v[36:39]
	v_mfma_f32_16x16x32_bf16 v[32:35], v[234:237], v[172:175], v[32:35]
	v_mfma_f32_16x16x32_bf16 v[20:23], v[226:229], v[210:213], v[20:23]
	v_mfma_f32_16x16x32_bf16 v[16:19], v[234:237], v[210:213], v[16:19]
	v_mfma_f32_16x16x32_bf16 v[4:7], v[226:229], v[218:221], v[4:7]
	v_mfma_f32_16x16x32_bf16 v[0:3], v[234:237], v[218:221], v[0:3]
	v_mfma_f32_16x16x32_bf16 v[52:55], v[230:233], v[168:171], v[52:55]
	v_mfma_f32_16x16x32_bf16 v[48:51], v[238:241], v[168:171], v[48:51]
	v_mfma_f32_16x16x32_bf16 v[36:39], v[230:233], v[186:189], v[36:39]
	v_mfma_f32_16x16x32_bf16 v[32:35], v[238:241], v[186:189], v[32:35]
	v_mfma_f32_16x16x32_bf16 v[20:23], v[230:233], v[214:217], v[20:23]
	v_mfma_f32_16x16x32_bf16 v[16:19], v[238:241], v[214:217], v[16:19]
	v_mfma_f32_16x16x32_bf16 v[4:7], v[230:233], v[222:225], v[4:7]
	v_mfma_f32_16x16x32_bf16 v[0:3], v[238:241], v[222:225], v[0:3]
	s_setprio 0
	s_add_u32 s20, s20, 0x100
	s_addc_u32 s21, s21, 0
	s_add_u32 s44, s44, 0x100
	s_addc_u32 s45, s45, 0
	s_cmp_ge_u32 s46, s55
	s_mov_b32 s22, s46
	s_barrier
	s_cbranch_scc0 .LBB0_1151
	s_lshl_b32 s21, s61, 8
	s_ashr_i32 s20, s61, 3
	s_add_i32 s22, s21, 0xffffc000
	v_readlane_b32 s68, v254, 60
	s_cmp_gt_i32 s61, 63
	s_mul_i32 s20, s20, 9
	v_readlane_b32 s80, v255, 8
	v_readlane_b32 s81, v255, 9
	v_readlane_b32 s82, v255, 10
	v_readlane_b32 s83, v255, 11
	s_cselect_b32 s24, 0x48, s20
	v_readlane_b32 s72, v255, 0
	v_readlane_b32 s73, v255, 1
	s_mov_b64 s[80:81], s[88:89]
	s_cselect_b32 s44, s22, s21
	s_cselect_b32 s21, s73, s50
	s_cselect_b32 s20, s72, s51
	s_cselect_b32 s23, 0, s81
	s_cselect_b32 s22, 0, s80
	s_add_i32 s24, s24, s52
	s_ashr_i32 s25, s24, 31
	s_mov_b64 s[82:83], s[90:91]
	s_lshl_b64 s[24:25], s[24:25], 13
	v_lshl_or_b32 v160, s66, 8, v165
	s_add_u32 s24, s82, s24
	s_addc_u32 s25, s83, s25
	v_ashrrev_i32_e32 v161, 31, v160
	v_lshl_add_u64 v[158:159], v[160:161], 2, s[24:25]
	global_load_dwordx4 v[142:145], v[158:159], off
	global_load_dwordx4 v[146:149], v[158:159], off offset:64
	global_load_dwordx4 v[150:153], v[158:159], off offset:512
	global_load_dwordx4 v[154:157], v[158:159], off offset:576
	v_mov_b32_e32 v135, v134
	v_add_u32_e32 v162, s44, v97
	v_lshlrev_b32_e32 v163, 11, v162
	v_add_u32_e32 v163, v163, v160
	v_lshlrev_b32_e32 v163, 2, v163
	global_load_dwordx4 v[210:213], v163, s[20:21]
	global_load_dwordx4 v[214:217], v163, s[20:21] offset:64
	global_load_dwordx4 v[218:221], v163, s[20:21] offset:512
	global_load_dwordx4 v[222:225], v163, s[20:21] offset:576
	s_add_u32 s20, s20, 0x20000
	s_addc_u32 s21, s21, 0
	s_nop 0
	global_load_dwordx4 v[226:229], v163, s[20:21]
	global_load_dwordx4 v[230:233], v163, s[20:21] offset:64
	global_load_dwordx4 v[234:237], v163, s[20:21] offset:512
	global_load_dwordx4 v[238:241], v163, s[20:21] offset:576
	s_add_u32 s20, s20, 0x20000
	s_addc_u32 s21, s21, 0
	s_nop 0
	global_load_dwordx4 v[168:171], v163, s[20:21]
	global_load_dwordx4 v[172:175], v163, s[20:21] offset:64
	global_load_dwordx4 v[186:189], v163, s[20:21] offset:512
	global_load_dwordx4 v[198:201], v163, s[20:21] offset:576
	s_add_u32 s20, s20, 0x20000
	s_addc_u32 s21, s21, 0
	s_nop 0
	s_and_b64 vcc, exec, s[42:43]
	s_mov_b32 s66, s59
	s_mov_b32 s61, s58
	v_readlane_b32 s69, v254, 61
	v_readlane_b32 s70, v254, 62
	v_readlane_b32 s71, v254, 63
	v_readlane_b32 s74, v255, 2
	v_readlane_b32 s75, v255, 3
	v_readlane_b32 s76, v255, 4
	v_readlane_b32 s77, v255, 5
	v_readlane_b32 s78, v255, 6
	v_readlane_b32 s79, v255, 7
	s_waitcnt vmcnt(12)
	v_pk_mul_f32 v[142:143], v[136:137], v[142:143]
	v_pk_mul_f32 v[144:145], v[134:135], v[144:145]
	v_pk_mul_f32 v[146:147], v[136:137], v[146:147]
	v_pk_mul_f32 v[148:149], v[134:135], v[148:149]
	v_pk_mul_f32 v[150:151], v[136:137], v[150:151]
	v_pk_mul_f32 v[152:153], v[134:135], v[152:153]
	v_pk_mul_f32 v[154:155], v[136:137], v[154:155]
	v_pk_mul_f32 v[156:157], v[134:135], v[156:157]
	s_waitcnt vmcnt(8)
;     __device__ __forceinline__ void operator()(const f32x4 (&acc)[2][2][4][2], const pg8::Unit& u, int wr, int wc, int fr, int fq) const {
;     ...
;         for (int ai = 0; ai < 2; ++ai)
; #pragma unroll
;             for (int m = 0; m < 4; ++m) {
;                 const size_t o = (size_t)(row0 + ai * 128 + m * 16) * DM + col0;
; #pragma unroll
;                 for (int bj = 0; bj < 2; ++bj)
; #pragma unroll
;                     for (int n = 0; n < 2; ++n) { const f32x4 r = *(const f32x4*)(rb + o + bj * 128 + n * 16); *(f32x4*)(ob + o + bj * 128 + n * 16) = r + gv[bj][n] * acc[ai][bj][m][n]; }
	v_pk_fma_f32 v[128:129], v[128:129], v[144:145], v[212:213]
	v_pk_fma_f32 v[126:127], v[126:127], v[142:143], v[210:211]
	v_pk_fma_f32 v[124:125], v[124:125], v[148:149], v[216:217]
	v_pk_fma_f32 v[122:123], v[122:123], v[146:147], v[214:215]
	v_pk_fma_f32 v[120:121], v[120:121], v[152:153], v[220:221]
	v_pk_fma_f32 v[118:119], v[118:119], v[150:151], v[218:219]
	v_pk_fma_f32 v[116:117], v[116:117], v[156:157], v[224:225]
	v_pk_fma_f32 v[114:115], v[114:115], v[154:155], v[222:223]
	global_store_dwordx4 v163, v[126:129], s[22:23]
	global_store_dwordx4 v163, v[122:125], s[22:23] offset:64
	global_store_dwordx4 v163, v[118:121], s[22:23] offset:512
	global_store_dwordx4 v163, v[114:117], s[22:23] offset:576
	s_add_u32 s22, s22, 0x20000
	s_addc_u32 s23, s23, 0
	s_nop 0
	global_load_dwordx4 v[210:213], v163, s[20:21]
	global_load_dwordx4 v[214:217], v163, s[20:21] offset:64
	global_load_dwordx4 v[218:221], v163, s[20:21] offset:512
	global_load_dwordx4 v[222:225], v163, s[20:21] offset:576
	s_add_u32 s20, s20, 0xa0000
	s_addc_u32 s21, s21, 0
	s_nop 0
	s_waitcnt vmcnt(12)
	v_pk_fma_f32 v[112:113], v[112:113], v[144:145], v[228:229]
	v_pk_fma_f32 v[110:111], v[110:111], v[142:143], v[226:227]
	v_pk_fma_f32 v[108:109], v[108:109], v[148:149], v[232:233]
	v_pk_fma_f32 v[106:107], v[106:107], v[146:147], v[230:231]
	v_pk_fma_f32 v[104:105], v[104:105], v[152:153], v[236:237]
	v_pk_fma_f32 v[102:103], v[102:103], v[150:151], v[234:235]
	v_pk_fma_f32 v[100:101], v[100:101], v[156:157], v[240:241]
	v_pk_fma_f32 v[98:99], v[98:99], v[154:155], v[238:239]
	global_store_dwordx4 v163, v[110:113], s[22:23]
	global_store_dwordx4 v163, v[106:109], s[22:23] offset:64
	global_store_dwordx4 v163, v[102:105], s[22:23] offset:512
	global_store_dwordx4 v163, v[98:101], s[22:23] offset:576
	s_add_u32 s22, s22, 0x20000
	s_addc_u32 s23, s23, 0
	s_nop 0
	global_load_dwordx4 v[226:229], v163, s[20:21]
	global_load_dwordx4 v[230:233], v163, s[20:21] offset:64
	global_load_dwordx4 v[234:237], v163, s[20:21] offset:512
	global_load_dwordx4 v[238:241], v163, s[20:21] offset:576
	s_add_u32 s20, s20, 0x20000
	s_addc_u32 s21, s21, 0
	s_nop 0
	s_waitcnt vmcnt(16)
	v_pk_fma_f32 v[94:95], v[94:95], v[144:145], v[170:171]
	v_pk_fma_f32 v[92:93], v[92:93], v[142:143], v[168:169]
	v_pk_fma_f32 v[90:91], v[90:91], v[148:149], v[174:175]
	v_pk_fma_f32 v[88:89], v[88:89], v[146:147], v[172:173]
	v_pk_fma_f32 v[86:87], v[86:87], v[152:153], v[188:189]
	v_pk_fma_f32 v[84:85], v[84:85], v[150:151], v[186:187]
	v_pk_fma_f32 v[82:83], v[82:83], v[156:157], v[200:201]
	v_pk_fma_f32 v[80:81], v[80:81], v[154:155], v[198:199]
	global_store_dwordx4 v163, v[92:95], s[22:23]
	global_store_dwordx4 v163, v[88:91], s[22:23] offset:64
	global_store_dwordx4 v163, v[84:87], s[22:23] offset:512
	global_store_dwordx4 v163, v[80:83], s[22:23] offset:576
	s_add_u32 s22, s22, 0x20000
	s_addc_u32 s23, s23, 0
	s_nop 0
	global_load_dwordx4 v[168:171], v163, s[20:21]
	global_load_dwordx4 v[172:175], v163, s[20:21] offset:64
	global_load_dwordx4 v[186:189], v163, s[20:21] offset:512
	global_load_dwordx4 v[198:201], v163, s[20:21] offset:576
	s_add_u32 s20, s20, 0x20000
	s_addc_u32 s21, s21, 0
	s_nop 0
	s_waitcnt vmcnt(16)
	v_pk_fma_f32 v[78:79], v[78:79], v[144:145], v[212:213]
	v_pk_fma_f32 v[76:77], v[76:77], v[142:143], v[210:211]
	v_pk_fma_f32 v[74:75], v[74:75], v[148:149], v[216:217]
	v_pk_fma_f32 v[72:73], v[72:73], v[146:147], v[214:215]
	v_pk_fma_f32 v[70:71], v[70:71], v[152:153], v[220:221]
	v_pk_fma_f32 v[68:69], v[68:69], v[150:151], v[218:219]
	v_pk_fma_f32 v[66:67], v[66:67], v[156:157], v[224:225]
	v_pk_fma_f32 v[64:65], v[64:65], v[154:155], v[222:223]
	global_store_dwordx4 v163, v[76:79], s[22:23]
	global_store_dwordx4 v163, v[72:75], s[22:23] offset:64
	global_store_dwordx4 v163, v[68:71], s[22:23] offset:512
	global_store_dwordx4 v163, v[64:67], s[22:23] offset:576
	s_add_u32 s22, s22, 0xa0000
	s_addc_u32 s23, s23, 0
	s_nop 0
	global_load_dwordx4 v[210:213], v163, s[20:21]
	global_load_dwordx4 v[214:217], v163, s[20:21] offset:64
	global_load_dwordx4 v[218:221], v163, s[20:21] offset:512
	global_load_dwordx4 v[222:225], v163, s[20:21] offset:576
	s_add_u32 s20, s20, 0x20000
	s_addc_u32 s21, s21, 0
	s_nop 0
	s_waitcnt vmcnt(16)
; #define PG8_WAIT_V(n) asm volatile("s_waitcnt vmcnt(" #n ")" ::: "memory")
; #define PG8_BAR __builtin_amdgcn_s_barrier()
; template <class Epi>
; __device__ __forceinline__ void gemm_phase(LAS unsigned char* lds, const Gemm g, const StaticOrder& S, const Epi& E) {
;     ...
;         E(acc, cur, wr, wc, fr, fq);
;         if (!has_next) break;
; #pragma unroll
;         for (int a = 0; a < 2; ++a)
; #pragma unroll
;             for (int b = 0; b < 2; ++b)
; #pragma unroll
;                 for (int m = 0; m < 4; ++m)
; #pragma unroll
;                     for (int n = 0; n < 2; ++n) acc[a][b][m][n] = (f32x4){0.f, 0.f, 0.f, 0.f};
;         cur = nxt; cA = nA; cB = nB; ++ui;
;     }
;     PG8_WAIT_V(0);
;     if (wr == 0) PG8_BAR;
;     PG8_BAR;
;     __device__ __forceinline__ void operator()(const f32x4 (&acc)[2][2][4][2], const pg8::Unit& u, int wr, int wc, int fr, int fq) const {
;     ...
;         for (int ai = 0; ai < 2; ++ai)
; #pragma unroll
;             for (int m = 0; m < 4; ++m) {
;                 const size_t o = (size_t)(row0 + ai * 128 + m * 16) * DM + col0;
; #pragma unroll
;                 for (int bj = 0; bj < 2; ++bj)
; #pragma unroll
;                     for (int n = 0; n < 2; ++n) { const f32x4 r = *(const f32x4*)(rb + o + bj * 128 + n * 16); *(f32x4*)(ob + o + bj * 128 + n * 16) = r + gv[bj][n] * acc[ai][bj][m][n]; }
	v_pk_fma_f32 v[62:63], v[62:63], v[144:145], v[228:229]
	v_pk_fma_f32 v[60:61], v[60:61], v[142:143], v[226:227]
	v_pk_fma_f32 v[58:59], v[58:59], v[148:149], v[232:233]
	v_pk_fma_f32 v[56:57], v[56:57], v[146:147], v[230:231]
	v_pk_fma_f32 v[54:55], v[54:55], v[152:153], v[236:237]
	v_pk_fma_f32 v[52:53], v[52:53], v[150:151], v[234:235]
	v_pk_fma_f32 v[50:51], v[50:51], v[156:157], v[240:241]
	v_pk_fma_f32 v[48:49], v[48:49], v[154:155], v[238:239]
	global_store_dwordx4 v163, v[60:63], s[22:23]
	global_store_dwordx4 v163, v[56:59], s[22:23] offset:64
	global_store_dwordx4 v163, v[52:55], s[22:23] offset:512
	global_store_dwordx4 v163, v[48:51], s[22:23] offset:576
	s_add_u32 s22, s22, 0x20000
	s_addc_u32 s23, s23, 0
	s_nop 0
	global_load_dwordx4 v[226:229], v163, s[20:21]
	global_load_dwordx4 v[230:233], v163, s[20:21] offset:64
	global_load_dwordx4 v[234:237], v163, s[20:21] offset:512
	global_load_dwordx4 v[238:241], v163, s[20:21] offset:576
	s_add_u32 s20, s20, 0x20000
	s_addc_u32 s21, s21, 0
	s_nop 0
	s_waitcnt vmcnt(16)
	v_pk_fma_f32 v[46:47], v[46:47], v[144:145], v[170:171]
	v_pk_fma_f32 v[44:45], v[44:45], v[142:143], v[168:169]
	v_pk_fma_f32 v[42:43], v[42:43], v[148:149], v[174:175]
	v_pk_fma_f32 v[40:41], v[40:41], v[146:147], v[172:173]
	v_pk_fma_f32 v[38:39], v[38:39], v[152:153], v[188:189]
	v_pk_fma_f32 v[36:37], v[36:37], v[150:151], v[186:187]
	v_pk_fma_f32 v[34:35], v[34:35], v[156:157], v[200:201]
	v_pk_fma_f32 v[32:33], v[32:33], v[154:155], v[198:199]
	global_store_dwordx4 v163, v[44:47], s[22:23]
	global_store_dwordx4 v163, v[40:43], s[22:23] offset:64
	global_store_dwordx4 v163, v[36:39], s[22:23] offset:512
	global_store_dwordx4 v163, v[32:35], s[22:23] offset:576
	s_add_u32 s22, s22, 0x20000
	s_addc_u32 s23, s23, 0
	s_nop 0
	s_waitcnt vmcnt(12)
	v_pk_fma_f32 v[30:31], v[30:31], v[144:145], v[212:213]
	v_pk_fma_f32 v[28:29], v[28:29], v[142:143], v[210:211]
	v_pk_fma_f32 v[26:27], v[26:27], v[148:149], v[216:217]
	v_pk_fma_f32 v[24:25], v[24:25], v[146:147], v[214:215]
	v_pk_fma_f32 v[22:23], v[22:23], v[152:153], v[220:221]
	v_pk_fma_f32 v[20:21], v[20:21], v[150:151], v[218:219]
	v_pk_fma_f32 v[18:19], v[18:19], v[156:157], v[224:225]
	v_pk_fma_f32 v[16:17], v[16:17], v[154:155], v[222:223]
	global_store_dwordx4 v163, v[28:31], s[22:23]
	global_store_dwordx4 v163, v[24:27], s[22:23] offset:64
	global_store_dwordx4 v163, v[20:23], s[22:23] offset:512
	global_store_dwordx4 v163, v[16:19], s[22:23] offset:576
	s_add_u32 s22, s22, 0x20000
	s_addc_u32 s23, s23, 0
	s_nop 0
	s_waitcnt vmcnt(8)
	v_pk_fma_f32 v[14:15], v[14:15], v[144:145], v[228:229]
	v_pk_fma_f32 v[12:13], v[12:13], v[142:143], v[226:227]
	v_pk_fma_f32 v[10:11], v[10:11], v[148:149], v[232:233]
	v_pk_fma_f32 v[8:9], v[8:9], v[146:147], v[230:231]
	v_pk_fma_f32 v[6:7], v[6:7], v[152:153], v[236:237]
	v_pk_fma_f32 v[4:5], v[4:5], v[150:151], v[234:235]
	v_pk_fma_f32 v[2:3], v[2:3], v[156:157], v[240:241]
	v_pk_fma_f32 v[0:1], v[0:1], v[154:155], v[238:239]
	global_store_dwordx4 v163, v[12:15], s[22:23]
	global_store_dwordx4 v163, v[8:11], s[22:23] offset:64
	global_store_dwordx4 v163, v[4:7], s[22:23] offset:512
	global_store_dwordx4 v163, v[0:3], s[22:23] offset:576
	s_mov_b64 s[22:23], s[18:19]
	s_mov_b64 s[20:21], s[16:17]
	s_cbranch_vccz .LBB0_1140
	s_waitcnt vmcnt(0)
	s_cmpk_gt_u32 s30, 0xff
	s_cbranch_scc1 .LBB0_1155
	s_barrier

;     ...
;                 const bool isctx = r >= NLAT; const float* xp = isctx ? src_c + (size_t)(r - NLAT) * DM : src_l + (size_t)r * DM;
; #pragma unroll
;                 for (int k = 0; k < 8; ++k) v[q][k] = *(const f32x4*)(xp + (k * 64 + lane) * 4);
;                 if (isctx && part) {
;                     const float* gt = mod + (size_t)(8 * NMOD + 2) * DM; const float* pp = part + (size_t)(r - NLAT) * DM;
; #pragma unroll
;                     for (int k = 0; k < 8; ++k) { const int c = (k * 64 + lane) * 4;
;                         const f32x4 sum = (*(const f32x4*)(pp + c) + *(const f32x4*)(pp + (size_t)NCTX * DM + c)) + (*(const f32x4*)(pp + (size_t)2 * NCTX * DM + c) + *(const f32x4*)(pp + (size_t)3 * NCTX * DM + c));
;                         v[q][k] += *(const f32x4*)(gt + c) * 0.5f * sum; }
.LBB0_1224:
	v_readlane_b32 s36, v254, 60
	v_readlane_b32 s41, v255, 1
	v_add_u32_e32 v64, 0xffffc000, v68
	v_cmp_lt_i32_e32 vcc, s85, v68
	v_mov_b32_e32 v34, s81
	v_readlane_b32 s40, v255, 0
	v_mov_b32_e32 v35, s41
	v_cndmask_b32_e64 v33, v69, 0, vcc
	v_cndmask_b32_e32 v32, v68, v64, vcc
	v_cndmask_b32_e32 v35, v34, v35, vcc
	v_mov_b32_e32 v34, s80
	v_mov_b32_e32 v36, s40
	v_cndmask_b32_e32 v34, v34, v36, vcc
	v_lshlrev_b64 v[32:33], 13, v[32:33]
	v_lshl_add_u64 v[32:33], v[34:35], 0, v[32:33]
	v_lshlrev_b32_e32 v124, 2, v70
	v_mov_b32_e32 v125, v96
	v_lshl_add_u64 v[34:35], v[32:33], 0, v[124:125]
	v_mov_b32_e32 v111, v96
	global_load_dwordx4 v[60:63], v[34:35], off
	global_load_dwordx4 v[56:59], v[34:35], off offset:1024
	global_load_dwordx4 v[52:55], v[34:35], off offset:2048
	global_load_dwordx4 v[48:51], v[34:35], off offset:3072
	v_lshl_add_u64 v[34:35], v[32:33], 0, v[110:111]
	v_mov_b32_e32 v113, v96
	v_mov_b32_e32 v115, v96
	v_mov_b32_e32 v117, v96
	v_lshl_add_u64 v[36:37], v[32:33], 0, v[112:113]
	global_load_dwordx4 v[44:47], v[34:35], off
	global_load_dwordx4 v[40:43], v[36:37], off
	v_lshl_add_u64 v[34:35], v[32:33], 0, v[114:115]
	v_lshl_add_u64 v[32:33], v[32:33], 0, v[116:117]
	global_load_dwordx4 v[36:39], v[34:35], off
	s_nop 0
	global_load_dwordx4 v[32:35], v[32:33], off
	v_mov_b32_e32 v65, v96
	v_readlane_b32 s37, v254, 61
	v_readlane_b32 s38, v254, 62
	v_readlane_b32 s39, v254, 63
	v_readlane_b32 s42, v255, 2
	v_readlane_b32 s43, v255, 3
	v_readlane_b32 s44, v255, 4
	v_readlane_b32 s45, v255, 5
	v_readlane_b32 s46, v255, 6
	v_readlane_b32 s47, v255, 7
	v_readlane_b32 s48, v255, 8
	v_readlane_b32 s49, v255, 9
	v_readlane_b32 s50, v255, 10
	v_readlane_b32 s51, v255, 11
	s_and_saveexec_b64 s[16:17], vcc
	s_cbranch_execz .LBB0_1226
	v_lshlrev_b64 v[64:65], 13, v[64:65]
	v_lshl_add_u64 v[128:129], s[0:1], 0, v[64:65]
	v_mov_b32_e32 v119, v96
	v_mov_b32_e32 v121, v96
	v_mov_b32_e32 v123, v96
	s_waitcnt lgkmcnt(0)
	v_lshl_add_u64 v[128:129], v[128:129], 0, v[124:125]
	s_mov_b64 s[18:19], 0x1000
	v_lshl_add_u64 v[128:129], v[128:129], 0, s[18:19]
	s_mov_b64 s[18:19], 0x1000000
	v_lshl_add_u64 v[126:127], v[128:129], 0, s[18:19]
	v_lshl_add_u64 v[66:67], v[126:127], 0, s[18:19]
	v_lshl_add_u64 v[64:65], v[66:67], 0, s[18:19]
	global_load_dwordx4 v[152:155], v[128:129], off offset:-4096
	global_load_dwordx4 v[156:159], v[126:127], off offset:-4096
	global_load_dwordx4 v[160:163], v[66:67], off offset:-4096
	global_load_dwordx4 v[164:167], v[64:65], off offset:-4096
	global_load_dwordx4 v[168:171], v[72:73], off
	global_load_dwordx4 v[172:175], v[128:129], off offset:-3072
	global_load_dwordx4 v[186:189], v[126:127], off offset:-3072
	global_load_dwordx4 v[198:201], v[66:67], off offset:-3072
	global_load_dwordx4 v[212:215], v[64:65], off offset:-3072
	global_load_dwordx4 v[216:219], v[74:75], off
	global_load_dwordx4 v[220:223], v[128:129], off offset:-2048
	global_load_dwordx4 v[224:227], v[126:127], off offset:-2048
	global_load_dwordx4 v[228:231], v[66:67], off offset:-2048
	global_load_dwordx4 v[232:235], v[64:65], off offset:-2048
	global_load_dwordx4 v[236:239], v[76:77], off
	global_load_dwordx4 v[240:243], v[128:129], off offset:-1024
	global_load_dwordx4 v[244:247], v[126:127], off offset:-1024
	global_load_dwordx4 v[248:251], v[66:67], off offset:-1024
	global_load_dwordx4 v[138:141], v[64:65], off offset:-1024
	global_load_dwordx4 v[142:145], v[78:79], off
	s_waitcnt vmcnt(15)
	v_pk_add_f32 v[152:153], v[152:153], v[156:157]
	v_pk_add_f32 v[154:155], v[154:155], v[158:159]
	v_pk_add_f32 v[160:161], v[160:161], v[164:165]
	v_pk_add_f32 v[162:163], v[162:163], v[166:167]
	v_pk_add_f32 v[152:153], v[152:153], v[160:161]
	v_pk_add_f32 v[154:155], v[154:155], v[162:163]
	v_pk_mul_f32 v[168:169], v[168:169], 0.5 op_sel_hi:[1,0]
	v_pk_mul_f32 v[170:171], v[170:171], 0.5 op_sel_hi:[1,0]
	v_pk_fma_f32 v[60:61], v[168:169], v[152:153], v[60:61]
	v_pk_fma_f32 v[62:63], v[170:171], v[154:155], v[62:63]
	s_waitcnt vmcnt(10)
	v_pk_add_f32 v[172:173], v[172:173], v[186:187]
	v_pk_add_f32 v[174:175], v[174:175], v[188:189]
	v_pk_add_f32 v[198:199], v[198:199], v[212:213]
	v_pk_add_f32 v[200:201], v[200:201], v[214:215]
	v_pk_add_f32 v[172:173], v[172:173], v[198:199]
	v_pk_add_f32 v[174:175], v[174:175], v[200:201]
	v_pk_mul_f32 v[216:217], v[216:217], 0.5 op_sel_hi:[1,0]
	v_pk_mul_f32 v[218:219], v[218:219], 0.5 op_sel_hi:[1,0]
	v_pk_fma_f32 v[56:57], v[216:217], v[172:173], v[56:57]
	v_pk_fma_f32 v[58:59], v[218:219], v[174:175], v[58:59]
	s_waitcnt vmcnt(5)
;     ...
;                 if (isctx && part) {
;                     const float* gt = mod + (size_t)(8 * NMOD + 2) * DM; const float* pp = part + (size_t)(r - NLAT) * DM;
; #pragma unroll
;                     for (int k = 0; k < 8; ++k) { const int c = (k * 64 + lane) * 4;
;                         const f32x4 sum = (*(const f32x4*)(pp + c) + *(const f32x4*)(pp + (size_t)NCTX * DM + c)) + (*(const f32x4*)(pp + (size_t)2 * NCTX * DM + c) + *(const f32x4*)(pp + (size_t)3 * NCTX * DM + c));
;                         v[q][k] += *(const f32x4*)(gt + c) * 0.5f * sum; }
	v_pk_add_f32 v[220:221], v[220:221], v[224:225]
	v_pk_add_f32 v[222:223], v[222:223], v[226:227]
	v_pk_add_f32 v[228:229], v[228:229], v[232:233]
	v_pk_add_f32 v[230:231], v[230:231], v[234:235]
	v_pk_add_f32 v[220:221], v[220:221], v[228:229]
	v_pk_add_f32 v[222:223], v[222:223], v[230:231]
	v_pk_mul_f32 v[236:237], v[236:237], 0.5 op_sel_hi:[1,0]
	v_pk_mul_f32 v[238:239], v[238:239], 0.5 op_sel_hi:[1,0]
	v_pk_fma_f32 v[52:53], v[236:237], v[220:221], v[52:53]
	v_pk_fma_f32 v[54:55], v[238:239], v[222:223], v[54:55]
	s_waitcnt vmcnt(0)
	v_pk_add_f32 v[240:241], v[240:241], v[244:245]
	v_pk_add_f32 v[242:243], v[242:243], v[246:247]
	v_pk_add_f32 v[248:249], v[248:249], v[138:139]
	v_pk_add_f32 v[250:251], v[250:251], v[140:141]
	v_pk_add_f32 v[240:241], v[240:241], v[248:249]
	v_pk_add_f32 v[242:243], v[242:243], v[250:251]
	v_pk_mul_f32 v[142:143], v[142:143], 0.5 op_sel_hi:[1,0]
	v_pk_mul_f32 v[144:145], v[144:145], 0.5 op_sel_hi:[1,0]
	v_pk_fma_f32 v[48:49], v[142:143], v[240:241], v[48:49]
	v_pk_fma_f32 v[50:51], v[144:145], v[242:243], v[50:51]
	global_load_dwordx4 v[152:155], v[128:129], off
	global_load_dwordx4 v[156:159], v[126:127], off
	global_load_dwordx4 v[160:163], v[66:67], off
	global_load_dwordx4 v[164:167], v[64:65], off
	global_load_dwordx4 v[168:171], v[80:81], off
	global_load_dwordx4 v[172:175], v[128:129], off offset:1024
	global_load_dwordx4 v[186:189], v[126:127], off offset:1024
	global_load_dwordx4 v[198:201], v[66:67], off offset:1024
	global_load_dwordx4 v[212:215], v[64:65], off offset:1024
	global_load_dwordx4 v[216:219], v[82:83], off
	global_load_dwordx4 v[220:223], v[128:129], off offset:2048
	global_load_dwordx4 v[224:227], v[126:127], off offset:2048
	global_load_dwordx4 v[228:231], v[66:67], off offset:2048
	global_load_dwordx4 v[232:235], v[64:65], off offset:2048
	global_load_dwordx4 v[236:239], v[84:85], off
	global_load_dwordx4 v[240:243], v[128:129], off offset:3072
	global_load_dwordx4 v[244:247], v[126:127], off offset:3072
	global_load_dwordx4 v[248:251], v[66:67], off offset:3072
	global_load_dwordx4 v[138:141], v[64:65], off offset:3072
	global_load_dwordx4 v[142:145], v[86:87], off
	s_waitcnt vmcnt(15)
	v_pk_add_f32 v[152:153], v[152:153], v[156:157]
	v_pk_add_f32 v[154:155], v[154:155], v[158:159]
	v_pk_add_f32 v[160:161], v[160:161], v[164:165]
	v_pk_add_f32 v[162:163], v[162:163], v[166:167]
	v_pk_add_f32 v[152:153], v[152:153], v[160:161]
	v_pk_add_f32 v[154:155], v[154:155], v[162:163]
	v_pk_mul_f32 v[168:169], v[168:169], 0.5 op_sel_hi:[1,0]
	v_pk_mul_f32 v[170:171], v[170:171], 0.5 op_sel_hi:[1,0]
	v_pk_fma_f32 v[44:45], v[168:169], v[152:153], v[44:45]
	v_pk_fma_f32 v[46:47], v[170:171], v[154:155], v[46:47]
	s_waitcnt vmcnt(10)
	v_pk_add_f32 v[172:173], v[172:173], v[186:187]
	v_pk_add_f32 v[174:175], v[174:175], v[188:189]
	v_pk_add_f32 v[198:199], v[198:199], v[212:213]
	v_pk_add_f32 v[200:201], v[200:201], v[214:215]
	v_pk_add_f32 v[172:173], v[172:173], v[198:199]
	v_pk_add_f32 v[174:175], v[174:175], v[200:201]
	v_pk_mul_f32 v[216:217], v[216:217], 0.5 op_sel_hi:[1,0]
	v_pk_mul_f32 v[218:219], v[218:219], 0.5 op_sel_hi:[1,0]
	v_pk_fma_f32 v[40:41], v[216:217], v[172:173], v[40:41]
	v_pk_fma_f32 v[42:43], v[218:219], v[174:175], v[42:43]
	s_waitcnt vmcnt(5)
	v_pk_add_f32 v[220:221], v[220:221], v[224:225]
	v_pk_add_f32 v[222:223], v[222:223], v[226:227]
	v_pk_add_f32 v[228:229], v[228:229], v[232:233]
	v_pk_add_f32 v[230:231], v[230:231], v[234:235]
	v_pk_add_f32 v[220:221], v[220:221], v[228:229]
	v_pk_add_f32 v[222:223], v[222:223], v[230:231]
	v_pk_mul_f32 v[236:237], v[236:237], 0.5 op_sel_hi:[1,0]
	v_pk_mul_f32 v[238:239], v[238:239], 0.5 op_sel_hi:[1,0]
	v_pk_fma_f32 v[36:37], v[236:237], v[220:221], v[36:37]
	v_pk_fma_f32 v[38:39], v[238:239], v[222:223], v[38:39]
	s_waitcnt vmcnt(0)
	v_pk_add_f32 v[240:241], v[240:241], v[244:245]
	v_pk_add_f32 v[242:243], v[242:243], v[246:247]
	v_pk_add_f32 v[248:249], v[248:249], v[138:139]
	v_pk_add_f32 v[250:251], v[250:251], v[140:141]
	v_pk_add_f32 v[240:241], v[240:241], v[248:249]
	v_pk_add_f32 v[242:243], v[242:243], v[250:251]
	v_pk_mul_f32 v[142:143], v[142:143], 0.5 op_sel_hi:[1,0]
	v_pk_mul_f32 v[144:145], v[144:145], 0.5 op_sel_hi:[1,0]
	v_pk_fma_f32 v[32:33], v[142:143], v[240:241], v[32:33]
	v_pk_fma_f32 v[34:35], v[144:145], v[242:243], v[34:35]
